# gla_c item: all 32 chunk-state fragment loads in flight (counted vmcnt) + 8 norm-gain quads preloaded, per-tile vmcnt(0) waits removed
# speedup vs baseline: 1.0565x; 1.0007x over previous
; __device__ __forceinline__ bf16_t f2bf(float f) { return (bf16_t)(pk2(f, f) & 0xffffu); }
; __device__ __forceinline__ void gla_c_item(const Params& P, int item, unsigned char* smem) {
;     ...
;     for (int d = 0; d < 2; ++d) {
;         const float gref = d == 0 ? gref0 : gref1;
; #pragma unroll
;         for (int ii = 0; ii < 16; ++ii) {
;             const int i = part * 16 + ii;
;             const float gc = d == 0 ? gc0[ii] : gc1[ii];
;             sQD[i * LROW + dk] = f2bf(qq[ii] * __expf(gc - gref));
;             sKD[i * LROW + dk] = f2bf(kk[ii] * __expf(gref - gc));
;             sQG[i * 136 + d * 64 + dk] = f2bf(qq[ii] * __expf(gc));
;         }
.LBB0_1320:
	s_or_b64 exec, exec, s[62:63]
	s_waitcnt lgkmcnt(1)
	v_add_f32_e32 v0, v2, v3
	v_add_f32_e32 v160, v4, v149
	v_add_f32_e32 v163, v17, v149
	s_waitcnt lgkmcnt(0)
	v_add_f32_e32 v17, v1, v148
	v_sub_f32_e32 v1, v160, v0
	v_mul_f32_e32 v1, 0x3fb8aa3b, v1
	v_exp_f32_e32 v1, v1
	v_lshlrev_b32_e32 v86, 16, v23
	v_lshlrev_b32_e32 v87, 16, v25
	v_add_f32_e32 v161, v19, v149
	v_mul_f32_e32 v1, v1, v86
	v_cvt_pk_bf16_f32 v1, v1, s0
	ds_write_b16 v99, v1 offset:10240
	v_sub_f32_e32 v1, v0, v160
	v_mul_f32_e32 v1, 0x3fb8aa3b, v1
	v_exp_f32_e32 v1, v1
	v_lshlrev_b32_e32 v83, 16, v28
	v_lshlrev_b32_e32 v85, 16, v29
	v_add_f32_e32 v162, v18, v149
	v_mul_f32_e32 v1, v1, v87
	v_cvt_pk_bf16_f32 v1, v1, s0
	ds_write_b16 v99, v1 offset:19456
	v_mul_f32_e32 v1, 0x3fb8aa3b, v160
	v_exp_f32_e32 v1, v1
	v_lshlrev_b32_e32 v79, 16, v30
	v_lshlrev_b32_e32 v81, 16, v31
	v_lshlrev_b32_e32 v76, 16, v32
	v_mul_f32_e32 v1, v1, v86
	v_cvt_pk_bf16_f32 v1, v1, s0
	ds_write_b16 v100, v1 offset:28672
	v_sub_f32_e32 v1, v161, v0
	v_mul_f32_e32 v1, 0x3fb8aa3b, v1
	v_exp_f32_e32 v1, v1
	v_lshlrev_b32_e32 v77, 16, v33
	v_add_f32_e32 v164, v16, v149
	v_lshlrev_b32_e32 v34, 16, v34
	v_mul_f32_e32 v1, v1, v83
	v_cvt_pk_bf16_f32 v1, v1, s0
	ds_write_b16 v101, v1 offset:10240
	v_sub_f32_e32 v1, v0, v161
	v_mul_f32_e32 v1, 0x3fb8aa3b, v1
	v_exp_f32_e32 v1, v1
	v_lshlrev_b32_e32 v35, 16, v35
	v_add_f32_e32 v15, v15, v149
	v_lshlrev_b32_e32 v45, 16, v45
	v_mul_f32_e32 v1, v1, v85
	v_cvt_pk_bf16_f32 v1, v1, s0
	ds_write_b16 v101, v1 offset:19456
	v_mul_f32_e32 v1, 0x3fb8aa3b, v161
	v_exp_f32_e32 v1, v1
	v_lshlrev_b32_e32 v47, 16, v47
	v_add_f32_e32 v14, v14, v149
	v_lshlrev_b32_e32 v49, 16, v49
	v_mul_f32_e32 v1, v1, v83
	v_cvt_pk_bf16_f32 v1, v1, s0
	ds_write_b16 v102, v1 offset:28672
	v_sub_f32_e32 v1, v162, v0
	v_mul_f32_e32 v1, 0x3fb8aa3b, v1
	v_exp_f32_e32 v1, v1
	v_lshlrev_b32_e32 v51, 16, v51
	v_add_f32_e32 v13, v13, v149
	v_lshlrev_b32_e32 v53, 16, v53
	v_mul_f32_e32 v1, v1, v79
	v_cvt_pk_bf16_f32 v1, v1, s0
	ds_write_b16 v103, v1 offset:10240
	v_sub_f32_e32 v1, v0, v162
	v_mul_f32_e32 v1, 0x3fb8aa3b, v1
	v_exp_f32_e32 v1, v1
	v_lshlrev_b32_e32 v55, 16, v55
	v_add_f32_e32 v12, v12, v149
	v_lshlrev_b32_e32 v57, 16, v57
	v_mul_f32_e32 v1, v1, v81
	v_cvt_pk_bf16_f32 v1, v1, s0
	ds_write_b16 v103, v1 offset:19456
	v_mul_f32_e32 v1, 0x3fb8aa3b, v162
	v_exp_f32_e32 v1, v1
	v_lshlrev_b32_e32 v59, 16, v59
	v_add_f32_e32 v11, v11, v149
	v_lshlrev_b32_e32 v61, 16, v61
	v_mul_f32_e32 v1, v1, v79
	v_cvt_pk_bf16_f32 v1, v1, s0
	ds_write_b16 v104, v1 offset:28672
	v_sub_f32_e32 v1, v163, v0
	v_mul_f32_e32 v1, 0x3fb8aa3b, v1
	v_exp_f32_e32 v1, v1
	v_lshlrev_b32_e32 v63, 16, v63
	v_add_f32_e32 v10, v10, v149
	v_lshlrev_b32_e32 v64, 16, v64
	v_mul_f32_e32 v1, v1, v76
	v_cvt_pk_bf16_f32 v1, v1, s0
	ds_write_b16 v105, v1 offset:10240
	v_sub_f32_e32 v1, v0, v163
	v_mul_f32_e32 v1, 0x3fb8aa3b, v1
	v_exp_f32_e32 v1, v1
	v_lshlrev_b32_e32 v65, 16, v65
	v_add_f32_e32 v9, v9, v149
	v_lshlrev_b32_e32 v66, 16, v66
	v_mul_f32_e32 v1, v1, v77
	v_cvt_pk_bf16_f32 v1, v1, s0
	ds_write_b16 v105, v1 offset:19456
	v_mul_f32_e32 v1, 0x3fb8aa3b, v163
	v_exp_f32_e32 v1, v1
	v_lshlrev_b32_e32 v67, 16, v67
	v_add_f32_e32 v8, v8, v149
	v_lshlrev_b32_e32 v68, 16, v68
	v_mul_f32_e32 v1, v1, v76
	v_cvt_pk_bf16_f32 v1, v1, s0
	ds_write_b16 v106, v1 offset:28672
	v_sub_f32_e32 v1, v164, v0
	v_mul_f32_e32 v1, 0x3fb8aa3b, v1
	v_exp_f32_e32 v1, v1
	v_lshlrev_b32_e32 v69, 16, v69
	v_add_f32_e32 v4, v7, v149
	v_lshlrev_b32_e32 v70, 16, v70
	v_mul_f32_e32 v1, v1, v34
	v_cvt_pk_bf16_f32 v1, v1, s0
	ds_write_b16 v107, v1 offset:10240
	v_sub_f32_e32 v1, v0, v164
	v_mul_f32_e32 v1, 0x3fb8aa3b, v1
	v_exp_f32_e32 v1, v1
	v_lshlrev_b32_e32 v71, 16, v71
	v_add_f32_e32 v3, v6, v149
	v_lshlrev_b32_e32 v72, 16, v72
	v_mul_f32_e32 v1, v1, v35
	v_cvt_pk_bf16_f32 v1, v1, s0
	ds_write_b16 v107, v1 offset:19456
	v_mul_f32_e32 v1, 0x3fb8aa3b, v164
	v_exp_f32_e32 v1, v1
	v_lshlrev_b32_e32 v73, 16, v73
	v_add_f32_e32 v2, v5, v149
	v_lshlrev_b32_e32 v36, 16, v74
	v_mul_f32_e32 v1, v1, v34
	v_cvt_pk_bf16_f32 v1, v1, s0
	ds_write_b16 v108, v1 offset:28672
	v_sub_f32_e32 v1, v15, v0
	v_mul_f32_e32 v1, 0x3fb8aa3b, v1
	v_exp_f32_e32 v1, v1
	v_lshlrev_b32_e32 v24, 16, v24
	v_add_f32_e32 v19, v147, v159
	v_add_f32_e32 v18, v146, v159
	v_mul_f32_e32 v1, v1, v45
	v_cvt_pk_bf16_f32 v1, v1, s0
	ds_write_b16 v109, v1 offset:10240
	v_sub_f32_e32 v1, v0, v15
	v_mul_f32_e32 v1, 0x3fb8aa3b, v1
	v_exp_f32_e32 v1, v1
	v_add_f32_e32 v32, v150, v159
	v_add_f32_e32 v31, v151, v159
	v_add_f32_e32 v30, v152, v159
	v_mul_f32_e32 v1, v1, v47
	v_cvt_pk_bf16_f32 v1, v1, s0
	ds_write_b16 v109, v1 offset:19456
	v_mul_f32_e32 v1, 0x3fb8aa3b, v15
	v_exp_f32_e32 v1, v1
	v_add_f32_e32 v29, v153, v159
	v_add_f32_e32 v144, v144, v159
	v_add_f32_e32 v16, v145, v159
	v_mul_f32_e32 v1, v1, v45
	v_cvt_pk_bf16_f32 v1, v1, s0
	ds_write_b16 v110, v1 offset:28672
	v_sub_f32_e32 v1, v14, v0
	v_mul_f32_e32 v1, 0x3fb8aa3b, v1
	v_exp_f32_e32 v1, v1
	v_sub_f32_e32 v145, v144, v17
	v_mul_f32_e32 v145, 0x3fb8aa3b, v145
	v_exp_f32_e32 v145, v145
	v_mul_f32_e32 v1, v1, v49
	v_cvt_pk_bf16_f32 v1, v1, s0
	ds_write_b16 v111, v1 offset:10240
	v_sub_f32_e32 v1, v0, v14
	v_mul_f32_e32 v1, 0x3fb8aa3b, v1
	v_exp_f32_e32 v1, v1
	v_mul_f32_e32 v145, v145, v86
	v_cvt_pk_bf16_f32 v145, v145, s0
	v_add_f32_e32 v84, v84, v159
	v_mul_f32_e32 v1, v1, v51
	v_cvt_pk_bf16_f32 v1, v1, s0
	ds_write_b16 v111, v1 offset:19456
	v_mul_f32_e32 v1, 0x3fb8aa3b, v14
	v_exp_f32_e32 v1, v1
	v_add_f32_e32 v82, v82, v159
	v_add_f32_e32 v78, v78, v159
	v_add_f32_e32 v74, v158, v159
	v_mul_f32_e32 v1, v1, v49
; __device__ __forceinline__ bf16_t f2bf(float f) { return (bf16_t)(pk2(f, f) & 0xffffu); }
; __device__ __forceinline__ void gla_c_item(const Params& P, int item, unsigned char* smem) {
;     ...
;     for (int d = 0; d < 2; ++d) {
;         const float gref = d == 0 ? gref0 : gref1;
; #pragma unroll
;         for (int ii = 0; ii < 16; ++ii) {
;             const int i = part * 16 + ii;
;             const float gc = d == 0 ? gc0[ii] : gc1[ii];
;             sQD[i * LROW + dk] = f2bf(qq[ii] * __expf(gc - gref));
;             sKD[i * LROW + dk] = f2bf(kk[ii] * __expf(gref - gc));
;             sQG[i * 136 + d * 64 + dk] = f2bf(qq[ii] * __expf(gc));
;         }
;         __syncthreads();
; #pragma unroll
;         for (int jt = 0; jt < 4; ++jt) {
;             f32x4 sc = (f32x4){0.f, 0.f, 0.f, 0.f};
; #pragma unroll
;             for (int ks = 0; ks < 2; ++ks) {
;                 const bf16x8 a = *(const bf16x8*)(sQD + (16 * w + fr) * LROW + ks * 32 + fq * 8);
;                 const bf16x8 bb = *(const bf16x8*)(sKD + (jt * 16 + fr) * LROW + ks * 32 + fq * 8);
;                 sc = __builtin_amdgcn_mfma_f32_16x16x32_bf16(a, bb, sc, 0, 0, 0);
;             }
; #pragma unroll
;             for (int r = 0; r < 4; ++r) {
;                 const int i = 16 * w + fq * 4 + r, j = jt * 16 + fr;
;                 const bool keep = d == 0 ? (j <= i) : (j >= i);
;                 pacc[jt][r] += keep ? sc[r] : 0.f;
;             }
;         }
	v_cvt_pk_bf16_f32 v1, v1, s0
	ds_write_b16 v112, v1 offset:28672
	v_sub_f32_e32 v1, v13, v0
	v_mul_f32_e32 v1, 0x3fb8aa3b, v1
	v_exp_f32_e32 v1, v1
	v_add_f32_e32 v33, v157, v159
	v_add_f32_e32 v28, v154, v159
	v_add_f32_e32 v25, v155, v159
	v_mul_f32_e32 v1, v1, v53
	v_cvt_pk_bf16_f32 v1, v1, s0
	ds_write_b16 v113, v1 offset:10240
	v_sub_f32_e32 v1, v0, v13
	v_mul_f32_e32 v1, 0x3fb8aa3b, v1
	v_exp_f32_e32 v1, v1
	v_add_f32_e32 v23, v156, v159
	s_add_i32 s77, s77, s76
	s_cmpk_gt_i32 s77, 0x7ff
	v_mul_f32_e32 v1, v1, v55
	v_cvt_pk_bf16_f32 v1, v1, s0
	ds_write_b16 v113, v1 offset:19456
	v_mul_f32_e32 v1, 0x3fb8aa3b, v13
	v_exp_f32_e32 v1, v1
	s_nop 0
	v_mul_f32_e32 v1, v1, v53
	v_cvt_pk_bf16_f32 v1, v1, s0
	ds_write_b16 v114, v1 offset:28672
	v_sub_f32_e32 v1, v12, v0
	v_mul_f32_e32 v1, 0x3fb8aa3b, v1
	v_exp_f32_e32 v1, v1
	s_nop 0
	v_mul_f32_e32 v1, v1, v57
	v_cvt_pk_bf16_f32 v1, v1, s0
	ds_write_b16 v115, v1 offset:10240
	v_sub_f32_e32 v1, v0, v12
	v_mul_f32_e32 v1, 0x3fb8aa3b, v1
	v_exp_f32_e32 v1, v1
	s_nop 0
	v_mul_f32_e32 v1, v1, v59
	v_cvt_pk_bf16_f32 v1, v1, s0
	ds_write_b16 v115, v1 offset:19456
	v_mul_f32_e32 v1, 0x3fb8aa3b, v12
	v_exp_f32_e32 v1, v1
	s_nop 0
	v_mul_f32_e32 v1, v1, v57
	v_cvt_pk_bf16_f32 v1, v1, s0
	ds_write_b16 v116, v1 offset:28672
	v_sub_f32_e32 v1, v11, v0
	v_mul_f32_e32 v1, 0x3fb8aa3b, v1
	v_exp_f32_e32 v1, v1
	s_nop 0
	v_mul_f32_e32 v1, v1, v61
	v_cvt_pk_bf16_f32 v1, v1, s0
	ds_write_b16 v117, v1 offset:10240
	v_sub_f32_e32 v1, v0, v11
	v_mul_f32_e32 v1, 0x3fb8aa3b, v1
	v_exp_f32_e32 v1, v1
	s_nop 0
	v_mul_f32_e32 v1, v1, v63
	v_cvt_pk_bf16_f32 v1, v1, s0
	ds_write_b16 v117, v1 offset:19456
	v_mul_f32_e32 v1, 0x3fb8aa3b, v11
	v_exp_f32_e32 v1, v1
	s_nop 0
	v_mul_f32_e32 v1, v1, v61
	v_cvt_pk_bf16_f32 v1, v1, s0
	ds_write_b16 v118, v1 offset:28672
	v_sub_f32_e32 v1, v10, v0
	v_mul_f32_e32 v1, 0x3fb8aa3b, v1
	v_exp_f32_e32 v1, v1
	s_nop 0
	v_mul_f32_e32 v1, v1, v64
	v_cvt_pk_bf16_f32 v1, v1, s0
	ds_write_b16 v119, v1 offset:10240
	v_sub_f32_e32 v1, v0, v10
	v_mul_f32_e32 v1, 0x3fb8aa3b, v1
	v_exp_f32_e32 v1, v1
	s_nop 0
	v_mul_f32_e32 v1, v1, v65
	v_cvt_pk_bf16_f32 v1, v1, s0
	ds_write_b16 v119, v1 offset:19456
	v_mul_f32_e32 v1, 0x3fb8aa3b, v10
	v_exp_f32_e32 v1, v1
	s_nop 0
	v_mul_f32_e32 v1, v1, v64
	v_cvt_pk_bf16_f32 v1, v1, s0
	ds_write_b16 v120, v1 offset:28672
	v_sub_f32_e32 v1, v9, v0
	v_mul_f32_e32 v1, 0x3fb8aa3b, v1
	v_exp_f32_e32 v1, v1
	s_nop 0
	v_mul_f32_e32 v1, v1, v66
	v_cvt_pk_bf16_f32 v1, v1, s0
	ds_write_b16 v121, v1 offset:10240
	v_sub_f32_e32 v1, v0, v9
	v_mul_f32_e32 v1, 0x3fb8aa3b, v1
	v_exp_f32_e32 v1, v1
	s_nop 0
	v_mul_f32_e32 v1, v1, v67
	v_cvt_pk_bf16_f32 v1, v1, s0
	ds_write_b16 v121, v1 offset:19456
	v_mul_f32_e32 v1, 0x3fb8aa3b, v9
	v_exp_f32_e32 v1, v1
	s_nop 0
	v_mul_f32_e32 v1, v1, v66
	v_cvt_pk_bf16_f32 v1, v1, s0
	ds_write_b16 v122, v1 offset:28672
	v_sub_f32_e32 v1, v8, v0
	v_mul_f32_e32 v1, 0x3fb8aa3b, v1
	v_exp_f32_e32 v1, v1
	s_nop 0
	v_mul_f32_e32 v1, v1, v68
	v_cvt_pk_bf16_f32 v1, v1, s0
	ds_write_b16 v123, v1 offset:10240
	v_sub_f32_e32 v1, v0, v8
	v_mul_f32_e32 v1, 0x3fb8aa3b, v1
	v_exp_f32_e32 v1, v1
	s_nop 0
	v_mul_f32_e32 v1, v1, v69
	v_cvt_pk_bf16_f32 v1, v1, s0
	ds_write_b16 v123, v1 offset:19456
	v_mul_f32_e32 v1, 0x3fb8aa3b, v8
	v_exp_f32_e32 v1, v1
	s_nop 0
	v_mul_f32_e32 v1, v1, v68
	v_cvt_pk_bf16_f32 v1, v1, s0
	ds_write_b16 v124, v1 offset:28672
	v_sub_f32_e32 v1, v4, v0
	v_mul_f32_e32 v1, 0x3fb8aa3b, v1
	v_exp_f32_e32 v1, v1
	s_nop 0
	v_mul_f32_e32 v1, v1, v70
	v_cvt_pk_bf16_f32 v1, v1, s0
	ds_write_b16 v125, v1 offset:10240
	v_sub_f32_e32 v1, v0, v4
	v_mul_f32_e32 v1, 0x3fb8aa3b, v1
	v_exp_f32_e32 v1, v1
	s_nop 0
	v_mul_f32_e32 v1, v1, v71
	v_cvt_pk_bf16_f32 v1, v1, s0
	ds_write_b16 v125, v1 offset:19456
	v_mul_f32_e32 v1, 0x3fb8aa3b, v4
	v_exp_f32_e32 v1, v1
	s_nop 0
	v_mul_f32_e32 v1, v1, v70
	v_cvt_pk_bf16_f32 v1, v1, s0
	ds_write_b16 v126, v1 offset:28672
	v_sub_f32_e32 v1, v3, v0
	v_mul_f32_e32 v1, 0x3fb8aa3b, v1
	v_exp_f32_e32 v1, v1
	s_nop 0
	v_mul_f32_e32 v1, v1, v72
	v_cvt_pk_bf16_f32 v1, v1, s0
	ds_write_b16 v127, v1 offset:10240
	v_sub_f32_e32 v1, v0, v3
	v_mul_f32_e32 v1, 0x3fb8aa3b, v1
	v_exp_f32_e32 v1, v1
	s_nop 0
	v_mul_f32_e32 v1, v1, v73
	v_cvt_pk_bf16_f32 v1, v1, s0
	ds_write_b16 v127, v1 offset:19456
	v_mul_f32_e32 v1, 0x3fb8aa3b, v3
	v_exp_f32_e32 v1, v1
	s_nop 0
	v_mul_f32_e32 v1, v1, v72
	v_cvt_pk_bf16_f32 v1, v1, s0
	ds_write_b16 v128, v1 offset:28672
	v_sub_f32_e32 v1, v2, v0
	v_sub_f32_e32 v0, v0, v2
	v_mul_f32_e32 v0, 0x3fb8aa3b, v0
	v_exp_f32_e32 v0, v0
	v_mul_f32_e32 v1, 0x3fb8aa3b, v1
	v_exp_f32_e32 v1, v1
	v_mul_f32_e32 v0, v0, v36
	v_cvt_pk_bf16_f32 v0, v0, s0
	ds_write_b16 v129, v0 offset:19456
	v_mul_f32_e32 v0, 0x3fb8aa3b, v2
	v_exp_f32_e32 v0, v0
	v_mul_f32_e32 v1, v1, v24
	v_cvt_pk_bf16_f32 v1, v1, s0
	ds_write_b16 v129, v1 offset:10240
	v_mul_f32_e32 v0, v0, v24
	v_cvt_pk_bf16_f32 v0, v0, s0
	ds_write_b16 v130, v0 offset:28672
	s_waitcnt lgkmcnt(0)
	s_barrier
	ds_read_b128 v[12:15], v98 offset:10240
	ds_read_b128 v[0:3], v131 offset:19456
	ds_read_b128 v[146:149], v98 offset:10304
	ds_read_b128 v[4:7], v131 offset:19520
	s_waitcnt lgkmcnt(2)
	v_mfma_f32_16x16x32_bf16 v[0:3], v[12:15], v[0:3], 0
	ds_read_b128 v[8:11], v131 offset:21824
	ds_read_b128 v[150:153], v131 offset:24128
	s_waitcnt lgkmcnt(2)
	v_mfma_f32_16x16x32_bf16 v[0:3], v[146:149], v[4:7], v[0:3]
	ds_read_b128 v[4:7], v131 offset:21760
	s_waitcnt lgkmcnt(0)
	v_mfma_f32_16x16x32_bf16 v[4:7], v[12:15], v[4:7], 0
	s_nop 4
	v_add_f32_e32 v3, 0, v3
	v_mfma_f32_16x16x32_bf16 v[4:7], v[146:149], v[8:11], v[4:7]
	ds_read_b128 v[8:11], v131 offset:24064
	v_cndmask_b32_e64 v3, v3, 0, s[48:49]
	v_add_f32_e32 v2, 0, v2
	s_waitcnt lgkmcnt(0)
	v_mfma_f32_16x16x32_bf16 v[8:11], v[12:15], v[8:11], 0
	v_cndmask_b32_e64 v2, v2, 0, s[52:53]
	s_nop 1
	v_add_f32_e32 v7, 0, v7
	v_cndmask_b32_e64 v7, v7, 0, s[34:35]
	v_mfma_f32_16x16x32_bf16 v[8:11], v[146:149], v[150:153], v[8:11]
	ds_read_b128 v[150:153], v131 offset:26368
	v_add_f32_e32 v6, 0, v6
	v_cndmask_b32_e64 v6, v6, 0, s[38:39]
	s_waitcnt lgkmcnt(0)
	v_mfma_f32_16x16x32_bf16 v[12:15], v[12:15], v[150:153], 0
	ds_read_b128 v[150:153], v131 offset:26432
	s_waitcnt lgkmcnt(0)
	s_barrier
; __device__ __forceinline__ bf16_t f2bf(float f) { return (bf16_t)(pk2(f, f) & 0xffffu); }
; __device__ __forceinline__ void gla_c_item(const Params& P, int item, unsigned char* smem) {
;     ...
;     for (int d = 0; d < 2; ++d) {
;         const float gref = d == 0 ? gref0 : gref1;
; #pragma unroll
;         for (int ii = 0; ii < 16; ++ii) {
;             const int i = part * 16 + ii;
;             const float gc = d == 0 ? gc0[ii] : gc1[ii];
;             sQD[i * LROW + dk] = f2bf(qq[ii] * __expf(gc - gref));
;             sKD[i * LROW + dk] = f2bf(kk[ii] * __expf(gref - gc));
;             sQG[i * 136 + d * 64 + dk] = f2bf(qq[ii] * __expf(gc));
;         }
;         __syncthreads();
; #pragma unroll
;         for (int jt = 0; jt < 4; ++jt) {
;             f32x4 sc = (f32x4){0.f, 0.f, 0.f, 0.f};
; #pragma unroll
;             for (int ks = 0; ks < 2; ++ks) {
;                 const bf16x8 a = *(const bf16x8*)(sQD + (16 * w + fr) * LROW + ks * 32 + fq * 8);
;                 const bf16x8 bb = *(const bf16x8*)(sKD + (jt * 16 + fr) * LROW + ks * 32 + fq * 8);
;                 sc = __builtin_amdgcn_mfma_f32_16x16x32_bf16(a, bb, sc, 0, 0, 0);
;             }
; #pragma unroll
;             for (int r = 0; r < 4; ++r) {
;                 const int i = 16 * w + fq * 4 + r, j = jt * 16 + fr;
;                 const bool keep = d == 0 ? (j <= i) : (j >= i);
;                 pacc[jt][r] += keep ? sc[r] : 0.f;
;             }
;         }
	ds_write_b16 v99, v145 offset:10240
	v_sub_f32_e32 v145, v17, v144
	v_mul_f32_e32 v145, 0x3fb8aa3b, v145
	v_exp_f32_e32 v145, v145
	v_mfma_f32_16x16x32_bf16 v[12:15], v[146:149], v[150:153], v[12:15]
	v_add_f32_e32 v11, 0, v11
	v_add_f32_e32 v10, 0, v10
	v_mul_f32_e32 v87, v145, v87
	v_cvt_pk_bf16_f32 v87, v87, s0
	ds_write_b16 v99, v87 offset:19456
	v_mul_f32_e32 v87, 0x3fb8aa3b, v144
	v_exp_f32_e32 v87, v87
	s_nop 0
	v_add_f32_e32 v14, 0, v14
	v_add_f32_e32 v13, 0, v13
	v_add_f32_e32 v12, 0, v12
	v_mul_f32_e32 v86, v87, v86
	v_cvt_pk_bf16_f32 v86, v86, s0
	ds_write_b16 v100, v86 offset:28800
	v_sub_f32_e32 v86, v84, v17
	v_mul_f32_e32 v86, 0x3fb8aa3b, v86
	v_exp_f32_e32 v86, v86
	v_cndmask_b32_e64 v12, v12, 0, vcc
	v_cndmask_b32_e64 v10, v10, 0, s[6:7]
	v_add_f32_e32 v9, 0, v9
	v_mul_f32_e32 v86, v86, v83
	v_cvt_pk_bf16_f32 v86, v86, s0
	ds_write_b16 v101, v86 offset:10240
	v_sub_f32_e32 v86, v17, v84
	v_mul_f32_e32 v86, 0x3fb8aa3b, v86
	v_mul_f32_e32 v84, 0x3fb8aa3b, v84
	v_exp_f32_e32 v86, v86
	v_exp_f32_e32 v84, v84
	v_cndmask_b32_e64 v9, v9, 0, s[26:27]
	v_add_f32_e32 v8, 0, v8
	v_mul_f32_e32 v85, v86, v85
	v_mul_f32_e32 v83, v84, v83
	v_cvt_pk_bf16_f32 v85, v85, s0
	v_cvt_pk_bf16_f32 v83, v83, s0
	ds_write_b16 v101, v85 offset:19456
	ds_write_b16 v102, v83 offset:28800
	v_sub_f32_e32 v83, v82, v17
	v_mul_f32_e32 v83, 0x3fb8aa3b, v83
	v_exp_f32_e32 v83, v83
	v_cndmask_b32_e64 v8, v8, 0, s[24:25]
	v_add_f32_e32 v5, 0, v5
	v_cndmask_b32_e64 v5, v5, 0, s[42:43]
	v_mul_f32_e32 v83, v83, v79
	v_cvt_pk_bf16_f32 v83, v83, s0
	ds_write_b16 v103, v83 offset:10240
	v_sub_f32_e32 v83, v17, v82
	v_mul_f32_e32 v83, 0x3fb8aa3b, v83
	v_exp_f32_e32 v83, v83
	v_add_f32_e32 v4, 0, v4
	v_cndmask_b32_e64 v4, v4, 0, s[40:41]
	v_add_f32_e32 v1, 0, v1
	v_mul_f32_e32 v81, v83, v81
	v_cvt_pk_bf16_f32 v81, v81, s0
	ds_write_b16 v103, v81 offset:19456
	v_mul_f32_e32 v81, 0x3fb8aa3b, v82
	v_exp_f32_e32 v81, v81
	v_cndmask_b32_e64 v1, v1, 0, s[56:57]
	v_add_f32_e32 v0, 0, v0
	v_cndmask_b32_e64 v0, v0, 0, s[54:55]
	v_mul_f32_e32 v79, v81, v79
	v_cvt_pk_bf16_f32 v79, v79, s0
	ds_write_b16 v104, v79 offset:28800
	v_sub_f32_e32 v79, v78, v17
	v_mul_f32_e32 v79, 0x3fb8aa3b, v79
	v_exp_f32_e32 v79, v79
	v_add_f32_e32 v15, 0, v15
	v_cndmask_b32_e64 v15, v15, 0, s[94:95]
	v_mul_f32_e32 v79, v79, v76
	v_cvt_pk_bf16_f32 v79, v79, s0
	ds_write_b16 v105, v79 offset:10240
	v_sub_f32_e32 v79, v17, v78
	v_mul_f32_e32 v79, 0x3fb8aa3b, v79
	v_exp_f32_e32 v79, v79
	s_nop 0
	v_mul_f32_e32 v77, v79, v77
	v_cvt_pk_bf16_f32 v77, v77, s0
	ds_write_b16 v105, v77 offset:19456
	v_mul_f32_e32 v77, 0x3fb8aa3b, v78
	v_exp_f32_e32 v77, v77
	s_nop 0
	v_mul_f32_e32 v76, v77, v76
	v_cvt_pk_bf16_f32 v76, v76, s0
	ds_write_b16 v106, v76 offset:28800
	v_sub_f32_e32 v76, v74, v17
	v_mul_f32_e32 v76, 0x3fb8aa3b, v76
	v_exp_f32_e32 v76, v76
	s_nop 0
	v_mul_f32_e32 v76, v76, v34
	v_cvt_pk_bf16_f32 v76, v76, s0
	ds_write_b16 v107, v76 offset:10240
	v_sub_f32_e32 v76, v17, v74
	v_mul_f32_e32 v76, 0x3fb8aa3b, v76
	v_exp_f32_e32 v76, v76
	s_nop 0
	v_mul_f32_e32 v35, v76, v35
	v_cvt_pk_bf16_f32 v35, v35, s0
	ds_write_b16 v107, v35 offset:19456
	v_mul_f32_e32 v35, 0x3fb8aa3b, v74
	v_exp_f32_e32 v35, v35
	s_nop 0
	v_mul_f32_e32 v34, v35, v34
	v_cvt_pk_bf16_f32 v34, v34, s0
	ds_write_b16 v108, v34 offset:28800
	v_sub_f32_e32 v34, v33, v17
	v_mul_f32_e32 v34, 0x3fb8aa3b, v34
	v_exp_f32_e32 v34, v34
	s_nop 0
	v_mul_f32_e32 v34, v34, v45
	v_cvt_pk_bf16_f32 v34, v34, s0
	ds_write_b16 v109, v34 offset:10240
	v_sub_f32_e32 v34, v17, v33
	v_mul_f32_e32 v34, 0x3fb8aa3b, v34
	v_mul_f32_e32 v33, 0x3fb8aa3b, v33
	v_exp_f32_e32 v34, v34
	v_exp_f32_e32 v33, v33
	v_mul_f32_e32 v34, v34, v47
	v_mul_f32_e32 v33, v33, v45
	v_cvt_pk_bf16_f32 v34, v34, s0
	v_cvt_pk_bf16_f32 v33, v33, s0
	ds_write_b16 v109, v34 offset:19456
	ds_write_b16 v110, v33 offset:28800
	v_sub_f32_e32 v33, v32, v17
	v_mul_f32_e32 v33, 0x3fb8aa3b, v33
	v_exp_f32_e32 v33, v33
	v_and_b32_e32 v47, 64, v141
	v_xor_b32_e32 v45, 16, v141
	v_add_u32_e32 v47, 64, v47
	v_mul_f32_e32 v33, v33, v49
	v_cvt_pk_bf16_f32 v33, v33, s0
	ds_write_b16 v111, v33 offset:10240
	v_sub_f32_e32 v33, v17, v32
	v_mul_f32_e32 v33, 0x3fb8aa3b, v33
	v_mul_f32_e32 v32, 0x3fb8aa3b, v32
	v_exp_f32_e32 v33, v33
	v_exp_f32_e32 v32, v32
	v_mul_f32_e32 v33, v33, v51
	v_mul_f32_e32 v32, v32, v49
	v_cvt_pk_bf16_f32 v33, v33, s0
	v_cvt_pk_bf16_f32 v32, v32, s0
	ds_write_b16 v111, v33 offset:19456
	ds_write_b16 v112, v32 offset:28800
	v_sub_f32_e32 v32, v31, v17
	v_mul_f32_e32 v32, 0x3fb8aa3b, v32
	v_exp_f32_e32 v32, v32
	v_mov_b32_e32 v49, v37
	v_mov_b32_e32 v51, v37
	v_mul_f32_e32 v32, v32, v53
	v_cvt_pk_bf16_f32 v32, v32, s0
	ds_write_b16 v113, v32 offset:10240
	v_sub_f32_e32 v32, v17, v31
	v_mul_f32_e32 v32, 0x3fb8aa3b, v32
	v_mul_f32_e32 v31, 0x3fb8aa3b, v31
	v_exp_f32_e32 v32, v32
	v_exp_f32_e32 v31, v31
	v_mul_f32_e32 v32, v32, v55
	v_mul_f32_e32 v31, v31, v53
	v_cvt_pk_bf16_f32 v32, v32, s0
	v_cvt_pk_bf16_f32 v31, v31, s0
	ds_write_b16 v113, v32 offset:19456
	ds_write_b16 v114, v31 offset:28800
	v_sub_f32_e32 v31, v30, v17
	v_mul_f32_e32 v31, 0x3fb8aa3b, v31
	v_exp_f32_e32 v31, v31
	v_mov_b32_e32 v53, v37
	v_mov_b32_e32 v55, v37
	v_mul_f32_e32 v31, v31, v57
	v_cvt_pk_bf16_f32 v31, v31, s0
	ds_write_b16 v115, v31 offset:10240
	v_sub_f32_e32 v31, v17, v30
	v_mul_f32_e32 v31, 0x3fb8aa3b, v31
	v_mul_f32_e32 v30, 0x3fb8aa3b, v30
	v_exp_f32_e32 v31, v31
	v_exp_f32_e32 v30, v30
	v_mul_f32_e32 v31, v31, v59
	v_mul_f32_e32 v30, v30, v57
	v_cvt_pk_bf16_f32 v31, v31, s0
	v_cvt_pk_bf16_f32 v30, v30, s0
	ds_write_b16 v115, v31 offset:19456
	ds_write_b16 v116, v30 offset:28800
	v_sub_f32_e32 v30, v29, v17
; __device__ __forceinline__ bf16_t f2bf(float f) { return (bf16_t)(pk2(f, f) & 0xffffu); }
; __device__ __forceinline__ void gla_c_item(const Params& P, int item, unsigned char* smem) {
;     ...
;     for (int d = 0; d < 2; ++d) {
;         const float gref = d == 0 ? gref0 : gref1;
; #pragma unroll
;         for (int ii = 0; ii < 16; ++ii) {
;             const int i = part * 16 + ii;
;             const float gc = d == 0 ? gc0[ii] : gc1[ii];
;             sQD[i * LROW + dk] = f2bf(qq[ii] * __expf(gc - gref));
;             sKD[i * LROW + dk] = f2bf(kk[ii] * __expf(gref - gc));
;             sQG[i * 136 + d * 64 + dk] = f2bf(qq[ii] * __expf(gc));
;         }
;         __syncthreads();
; #pragma unroll
;         for (int jt = 0; jt < 4; ++jt) {
;             f32x4 sc = (f32x4){0.f, 0.f, 0.f, 0.f};
; #pragma unroll
;             for (int ks = 0; ks < 2; ++ks) {
;                 const bf16x8 a = *(const bf16x8*)(sQD + (16 * w + fr) * LROW + ks * 32 + fq * 8);
;                 const bf16x8 bb = *(const bf16x8*)(sKD + (jt * 16 + fr) * LROW + ks * 32 + fq * 8);
;                 sc = __builtin_amdgcn_mfma_f32_16x16x32_bf16(a, bb, sc, 0, 0, 0);
;             }
; #pragma unroll
;             for (int r = 0; r < 4; ++r) {
;                 const int i = 16 * w + fq * 4 + r, j = jt * 16 + fr;
;                 const bool keep = d == 0 ? (j <= i) : (j >= i);
;                 pacc[jt][r] += keep ? sc[r] : 0.f;
;             }
;         }
	v_mul_f32_e32 v30, 0x3fb8aa3b, v30
	v_exp_f32_e32 v30, v30
	v_mov_b32_e32 v57, v37
	v_mov_b32_e32 v59, v37
	v_mul_f32_e32 v30, v30, v61
	v_cvt_pk_bf16_f32 v30, v30, s0
	ds_write_b16 v117, v30 offset:10240
	v_sub_f32_e32 v30, v17, v29
	v_mul_f32_e32 v30, 0x3fb8aa3b, v30
	v_mul_f32_e32 v29, 0x3fb8aa3b, v29
	v_exp_f32_e32 v30, v30
	v_exp_f32_e32 v29, v29
	v_mul_f32_e32 v30, v30, v63
	v_mul_f32_e32 v29, v29, v61
	v_cvt_pk_bf16_f32 v30, v30, s0
	v_cvt_pk_bf16_f32 v29, v29, s0
	ds_write_b16 v117, v30 offset:19456
	ds_write_b16 v118, v29 offset:28800
	v_sub_f32_e32 v29, v28, v17
	v_mul_f32_e32 v29, 0x3fb8aa3b, v29
	v_exp_f32_e32 v29, v29
	v_mov_b32_e32 v61, v37
	v_mov_b32_e32 v63, v37
	v_mul_f32_e32 v29, v29, v64
	v_cvt_pk_bf16_f32 v29, v29, s0
	ds_write_b16 v119, v29 offset:10240
	v_sub_f32_e32 v29, v17, v28
	v_mul_f32_e32 v29, 0x3fb8aa3b, v29
	v_mul_f32_e32 v28, 0x3fb8aa3b, v28
	v_exp_f32_e32 v29, v29
	v_exp_f32_e32 v28, v28
	v_mul_f32_e32 v29, v29, v65
	v_mul_f32_e32 v28, v28, v64
	v_cvt_pk_bf16_f32 v29, v29, s0
	v_cvt_pk_bf16_f32 v28, v28, s0
	ds_write_b16 v119, v29 offset:19456
	ds_write_b16 v120, v28 offset:28800
	v_sub_f32_e32 v28, v25, v17
	v_mul_f32_e32 v28, 0x3fb8aa3b, v28
	v_exp_f32_e32 v28, v28
	s_nop 0
	v_mul_f32_e32 v28, v28, v66
	v_cvt_pk_bf16_f32 v28, v28, s0
	ds_write_b16 v121, v28 offset:10240
	v_sub_f32_e32 v28, v17, v25
	v_mul_f32_e32 v28, 0x3fb8aa3b, v28
	v_mul_f32_e32 v25, 0x3fb8aa3b, v25
	v_exp_f32_e32 v28, v28
	v_exp_f32_e32 v25, v25
	v_mul_f32_e32 v28, v28, v67
	v_mul_f32_e32 v25, v25, v66
	v_cvt_pk_bf16_f32 v28, v28, s0
	v_cvt_pk_bf16_f32 v25, v25, s0
	ds_write_b16 v121, v28 offset:19456
	ds_write_b16 v122, v25 offset:28800
	v_sub_f32_e32 v25, v23, v17
	v_mul_f32_e32 v25, 0x3fb8aa3b, v25
	v_exp_f32_e32 v25, v25
	s_nop 0
	v_mul_f32_e32 v25, v25, v68
	v_cvt_pk_bf16_f32 v25, v25, s0
	ds_write_b16 v123, v25 offset:10240
	v_sub_f32_e32 v25, v17, v23
	v_mul_f32_e32 v25, 0x3fb8aa3b, v25
	v_mul_f32_e32 v23, 0x3fb8aa3b, v23
	v_exp_f32_e32 v25, v25
	v_exp_f32_e32 v23, v23
	v_mul_f32_e32 v25, v25, v69
	v_mul_f32_e32 v23, v23, v68
	v_cvt_pk_bf16_f32 v25, v25, s0
	v_cvt_pk_bf16_f32 v23, v23, s0
	ds_write_b16 v123, v25 offset:19456
	ds_write_b16 v124, v23 offset:28800
	v_sub_f32_e32 v23, v19, v17
	v_mul_f32_e32 v23, 0x3fb8aa3b, v23
	v_exp_f32_e32 v23, v23
	s_nop 0
	v_mul_f32_e32 v23, v23, v70
	v_cvt_pk_bf16_f32 v23, v23, s0
	ds_write_b16 v125, v23 offset:10240
	v_sub_f32_e32 v23, v17, v19
	v_mul_f32_e32 v23, 0x3fb8aa3b, v23
	v_mul_f32_e32 v19, 0x3fb8aa3b, v19
	v_exp_f32_e32 v23, v23
	v_exp_f32_e32 v19, v19
	v_mul_f32_e32 v23, v23, v71
	v_mul_f32_e32 v19, v19, v70
	v_cvt_pk_bf16_f32 v23, v23, s0
	v_cvt_pk_bf16_f32 v19, v19, s0
	ds_write_b16 v125, v23 offset:19456
	ds_write_b16 v126, v19 offset:28800
	v_sub_f32_e32 v19, v18, v17
	v_mul_f32_e32 v19, 0x3fb8aa3b, v19
	v_exp_f32_e32 v19, v19
	s_nop 0
	v_mul_f32_e32 v19, v19, v72
	v_cvt_pk_bf16_f32 v19, v19, s0
	ds_write_b16 v127, v19 offset:10240
	v_sub_f32_e32 v19, v17, v18
	v_mul_f32_e32 v19, 0x3fb8aa3b, v19
	v_mul_f32_e32 v18, 0x3fb8aa3b, v18
	v_exp_f32_e32 v19, v19
	v_exp_f32_e32 v18, v18
	v_mul_f32_e32 v19, v19, v73
	v_mul_f32_e32 v18, v18, v72
	v_cvt_pk_bf16_f32 v19, v19, s0
	v_cvt_pk_bf16_f32 v18, v18, s0
	ds_write_b16 v127, v19 offset:19456
	ds_write_b16 v128, v18 offset:28800
	v_sub_f32_e32 v18, v16, v17
	v_sub_f32_e32 v17, v17, v16
	v_mul_f32_e32 v18, 0x3fb8aa3b, v18
	v_mul_f32_e32 v17, 0x3fb8aa3b, v17
	v_mul_f32_e32 v16, 0x3fb8aa3b, v16
	v_exp_f32_e32 v18, v18
	v_exp_f32_e32 v17, v17
	v_exp_f32_e32 v16, v16
	v_mul_f32_e32 v18, v18, v24
	v_mul_f32_e32 v17, v17, v36
	v_mul_f32_e32 v16, v16, v24
	v_cvt_pk_bf16_f32 v18, v18, s0
	v_cvt_pk_bf16_f32 v17, v17, s0
	v_cvt_pk_bf16_f32 v16, v16, s0
	ds_write_b16 v129, v18 offset:10240
	ds_write_b16 v129, v17 offset:19456
	ds_write_b16 v130, v16 offset:28800
	s_waitcnt lgkmcnt(0)
	s_barrier
	ds_read_b128 v[16:19], v98 offset:10240
	ds_read_b128 v[28:31], v131 offset:19456
	ds_read_b128 v[32:35], v98 offset:10304
	ds_read_b128 v[64:67], v131 offset:19520
	s_waitcnt lgkmcnt(2)
	v_mfma_f32_16x16x32_bf16 v[28:31], v[16:19], v[28:31], 0
	ds_read_b128 v[68:71], v131 offset:21824
	ds_read_b128 v[76:79], v131 offset:24128
	v_readlane_b32 s0, v251, 5
	s_waitcnt lgkmcnt(2)
	v_mfma_f32_16x16x32_bf16 v[28:31], v[32:35], v[64:67], v[28:31]
	ds_read_b128 v[64:67], v131 offset:21760
	v_readlane_b32 s1, v251, 6
	v_lshlrev_b32_e32 v36, 1, v80
	s_waitcnt lgkmcnt(0)
	v_mfma_f32_16x16x32_bf16 v[64:67], v[16:19], v[64:67], 0
	v_mfma_f32_16x16x32_bf16 v[64:67], v[32:35], v[68:71], v[64:67]
	ds_read_b128 v[68:71], v131 offset:24064
	s_waitcnt lgkmcnt(0)
	v_mfma_f32_16x16x32_bf16 v[68:71], v[16:19], v[68:71], 0
	v_mfma_f32_16x16x32_bf16 v[68:71], v[32:35], v[76:79], v[68:71]
	ds_read_b128 v[76:79], v131 offset:26368
	s_waitcnt lgkmcnt(0)
	v_mfma_f32_16x16x32_bf16 v[16:19], v[16:19], v[76:79], 0
	ds_read_b128 v[76:79], v131 offset:26432
	s_waitcnt lgkmcnt(0)
; __device__ __forceinline__ bf16_t f2bf(float f) { return (bf16_t)(pk2(f, f) & 0xffffu); }
; __device__ __forceinline__ void gla_c_item(const Params& P, int item, unsigned char* smem) {
;     ...
; #pragma unroll
;     for (int jt = 0; jt < 4; ++jt)
; #pragma unroll
;         for (int r = 0; r < 4; ++r) sP[(16 * w + fq * 4 + r) * LROW + jt * 16 + fr] = f2bf(pacc[jt][r]);
;     const bf16_t* SS0 = (const bf16_t*)(P.ws + OFF_H) + ((size_t)(((b * 4 + h) * 2 + 0) * 132 + 4 + m)) * 8192;
;     const bf16_t* SS1 = (const bf16_t*)(P.ws + OFF_H) + ((size_t)(((b * 4 + h) * 2 + 1) * 132 + 4 + m)) * 8192;
;     const int i_out = 16 * w + fr;
;     const int tok_out = b * 8192 + ((m & 1) * 64 + i_out) * 64 + (m >> 1);
;     bf16_t* YB = (bf16_t*)(P.ws + OFF_YB);
;     uint2 rgr[8];
; #pragma unroll
;     for (int dvt = 0; dvt < 8; ++dvt) rgr[dvt] = *(const uint2*)(R + (size_t)(rowbase + i_out) * 512 + h * 128 + dvt * 16 + fq * 4);
;     __syncthreads();
;     f32x4 oacc[8];
; #pragma unroll
;     for (int dvt = 0; dvt < 8; ++dvt) oacc[dvt] = (f32x4){0.f, 0.f, 0.f, 0.f};
; #pragma unroll
;     for (int ks = 0; ks < 4; ++ks) {
;         const bf16x8 qb = *(const bf16x8*)(sQG + (16 * w + fr) * 136 + ks * 32 + fq * 8);
;         const bf16_t* SS = (ks >> 1) ? SS1 : SS0;
; #pragma unroll
;         for (int dvt = 0; dvt < 8; ++dvt) {
;             const bf16x8 sa = *(const bf16x8*)(SS + (size_t)(dvt * 16 + fr) * 64 + (ks & 1) * 32 + fq * 8);
;             oacc[dvt] = __builtin_amdgcn_mfma_f32_16x16x32_bf16(sa, qb, oacc[dvt], 0, 0, 0);
;         }
;     }
	v_mfma_f32_16x16x32_bf16 v[16:19], v[32:35], v[76:79], v[16:19]
	s_nop 7
	v_cndmask_b32_e64 v18, v18, 0, s[0:1]
	v_readlane_b32 s0, v251, 56
	v_readlane_b32 s1, v251, 57
	v_cndmask_b32_e32 v17, 0, v17, vcc
	v_cndmask_b32_e64 v19, v19, 0, s[86:87]
	v_cndmask_b32_e64 v14, v14, 0, s[0:1]
	v_readlane_b32 s0, v251, 58
	v_readlane_b32 s1, v251, 59
	v_add_f32_e32 v14, v14, v18
	v_add_f32_e32 v15, v15, v19
	v_cndmask_b32_e64 v13, v13, 0, s[0:1]
	v_readlane_b32 s0, v251, 60
	v_readlane_b32 s1, v251, 61
	v_add_f32_e32 v13, v13, v17
	s_nop 0
	v_cndmask_b32_e64 v16, v16, 0, s[0:1]
	v_readlane_b32 s0, v251, 62
	v_readlane_b32 s1, v251, 63
	v_add_f32_e32 v12, v12, v16
	s_nop 0
	v_cndmask_b32_e64 v16, v71, 0, s[0:1]
	v_readlane_b32 s0, v250, 0
	v_readlane_b32 s1, v250, 1
	s_nop 1
	v_cndmask_b32_e64 v11, v11, 0, s[0:1]
	v_readlane_b32 s0, v250, 2
	v_readlane_b32 s1, v250, 3
	v_add_f32_e32 v11, v11, v16
	s_nop 0
	v_cndmask_b32_e64 v16, v70, 0, s[0:1]
	v_add_f32_e32 v10, v10, v16
	v_cndmask_b32_e64 v16, 0, v69, s[24:25]
	v_add_f32_e32 v9, v9, v16
	v_cndmask_b32_e64 v16, v68, 0, s[28:29]
	v_add_f32_e32 v8, v8, v16
	v_cndmask_b32_e64 v16, v67, 0, s[30:31]
	v_add_f32_e32 v7, v7, v16
	v_cndmask_b32_e64 v16, v66, 0, s[36:37]
	v_add_f32_e32 v6, v6, v16
	v_cndmask_b32_e64 v16, 0, v65, s[40:41]
	v_add_f32_e32 v5, v5, v16
	v_cndmask_b32_e64 v16, v64, 0, s[44:45]
	v_add_f32_e32 v4, v4, v16
	v_cndmask_b32_e64 v16, v31, 0, s[46:47]
	v_add_f32_e32 v3, v3, v16
	v_cndmask_b32_e64 v16, v30, 0, s[50:51]
	v_add_f32_e32 v2, v2, v16
	v_cndmask_b32_e64 v16, 0, v29, s[54:55]
	v_add_f32_e32 v1, v1, v16
	v_cndmask_b32_e64 v16, v28, 0, s[58:59]
	v_add_f32_e32 v0, v0, v16
	v_cvt_pk_bf16_f32 v0, v0, s0
	ds_write_b16 v132, v0 offset:46080
	v_cvt_pk_bf16_f32 v0, v1, s0
	ds_write_b16 v133, v0 offset:46080
	v_cvt_pk_bf16_f32 v0, v2, s0
	ds_write_b16 v134, v0 offset:46080
	v_cvt_pk_bf16_f32 v0, v3, s0
	ds_write_b16 v135, v0 offset:46080
	v_cvt_pk_bf16_f32 v0, v4, s0
	ds_write_b16 v132, v0 offset:46112
	v_cvt_pk_bf16_f32 v0, v5, s0
	ds_write_b16 v133, v0 offset:46112
	v_cvt_pk_bf16_f32 v0, v6, s0
	ds_write_b16 v134, v0 offset:46112
	v_cvt_pk_bf16_f32 v0, v7, s0
	ds_write_b16 v135, v0 offset:46112
	v_cvt_pk_bf16_f32 v0, v8, s0
	ds_write_b16 v132, v0 offset:46144
	v_cvt_pk_bf16_f32 v0, v9, s0
	ds_write_b16 v133, v0 offset:46144
	v_cvt_pk_bf16_f32 v0, v10, s0
	ds_write_b16 v134, v0 offset:46144
	v_cvt_pk_bf16_f32 v0, v11, s0
	ds_write_b16 v135, v0 offset:46144
	v_cvt_pk_bf16_f32 v0, v12, s0
	ds_write_b16 v132, v0 offset:46176
	v_cvt_pk_bf16_f32 v0, v13, s0
	ds_write_b16 v133, v0 offset:46176
	v_cvt_pk_bf16_f32 v0, v14, s0
	ds_write_b16 v134, v0 offset:46176
	v_cvt_pk_bf16_f32 v0, v15, s0
	ds_write_b16 v135, v0 offset:46176
	v_lshlrev_b32_e32 v0, 3, v27
	v_lshl_or_b32 v6, v21, 1, v0
	v_lshrrev_b32_e32 v0, 1, v20
	v_or3_b32 v32, v0, v136, v26
	v_or_b32_e32 v0, v22, v97
	v_ashrrev_i32_e32 v1, 31, v0
	v_lshlrev_b64 v[0:1], 10, v[0:1]
	v_lshl_add_u64 v[0:1], s[84:85], 0, v[0:1]
	v_lshl_add_u64 v[0:1], v[0:1], 0, v[36:37]
	v_lshl_add_u64 v[0:1], v[0:1], 0, v[48:49]
	s_movk_i32 s0, 0x84
	global_load_dwordx2 v[34:35], v[0:1], off
	global_load_dwordx2 v[78:79], v[0:1], off offset:32
	global_load_dwordx2 v[76:77], v[0:1], off offset:64
	global_load_dwordx2 v[72:73], v[0:1], off offset:96
	global_load_dwordx2 v[70:71], v[0:1], off offset:128
	global_load_dwordx2 v[68:69], v[0:1], off offset:160
	global_load_dwordx2 v[66:67], v[0:1], off offset:192
	global_load_dwordx2 v[64:65], v[0:1], off offset:224
	v_mad_u64_u32 v[0:1], s[0:1], v6, s0, v[20:21]
	v_add_u32_e32 v6, 4, v0
	v_ashrrev_i32_e32 v7, 31, v6
	v_lshlrev_b64 v[6:7], 14, v[6:7]
	v_lshl_add_u64 v[30:31], v[40:41], 0, v[6:7]
	v_lshl_add_u64 v[86:87], v[30:31], 0, v[50:51]
	v_lshl_add_u64 v[14:15], v[30:31], 0, v[52:53]
	v_lshl_add_u64 v[18:19], v[30:31], 0, v[54:55]
	v_lshl_add_u64 v[22:23], v[30:31], 0, v[56:57]
	v_lshl_add_u64 v[26:27], v[30:31], 0, v[58:59]
	v_lshl_add_u64 v[82:83], v[30:31], 0, v[60:61]
	v_lshl_add_u64 v[144:145], v[30:31], 0, v[62:63]
	s_waitcnt lgkmcnt(0)
	s_barrier
	v_add_u32_e32 v248, 0x88, v0
	v_ashrrev_i32_e32 v249, 31, v248
	v_lshlrev_b64 v[248:249], 14, v[248:249]
	v_lshl_add_u64 v[248:249], v[40:41], 0, v[248:249]
	global_load_dwordx4 v[176:179], v[86:87], off offset:64
	global_load_dwordx4 v[180:183], v[86:87], off offset:2112
	global_load_dwordx4 v[184:187], v[14:15], off offset:64
	global_load_dwordx4 v[188:191], v[18:19], off offset:64
	global_load_dwordx4 v[192:195], v[22:23], off offset:64
	global_load_dwordx4 v[196:199], v[26:27], off offset:64
	global_load_dwordx4 v[200:203], v[82:83], off offset:64
	global_load_dwordx4 v[204:207], v[144:145], off offset:64
	global_load_dwordx4 v[4:7], v[86:87], off
	global_load_dwordx4 v[8:11], v[86:87], off offset:2048
	global_load_dwordx4 v[12:15], v[14:15], off
	global_load_dwordx4 v[16:19], v[18:19], off
	global_load_dwordx4 v[20:23], v[22:23], off
	global_load_dwordx4 v[24:27], v[26:27], off
	global_load_dwordx4 v[28:31], v[82:83], off
	global_load_dwordx4 v[0:3], v[144:145], off
	ds_read_b128 v[82:85], v137 offset:28672
	ds_read_b128 v[144:147], v137 offset:28736
	v_lshl_add_u64 v[86:87], v[248:249], 0, v[50:51]
	global_load_dwordx4 v[208:211], v[86:87], off
	global_load_dwordx4 v[240:243], v[86:87], off offset:64
	global_load_dwordx4 v[212:215], v[86:87], off offset:2048
	global_load_dwordx4 v[244:247], v[86:87], off offset:2112
	v_lshl_add_u64 v[86:87], v[248:249], 0, v[52:53]
	global_load_dwordx4 v[216:219], v[86:87], off
	global_load_dwordx4 v[156:159], v[86:87], off offset:64
	v_lshl_add_u64 v[86:87], v[248:249], 0, v[54:55]
	global_load_dwordx4 v[220:223], v[86:87], off
	global_load_dwordx4 v[160:163], v[86:87], off offset:64
	v_lshl_add_u64 v[86:87], v[248:249], 0, v[56:57]
	global_load_dwordx4 v[224:227], v[86:87], off
	global_load_dwordx4 v[164:167], v[86:87], off offset:64
	v_lshl_add_u64 v[86:87], v[248:249], 0, v[58:59]
	global_load_dwordx4 v[228:231], v[86:87], off
	global_load_dwordx4 v[172:175], v[86:87], off offset:64
	v_lshl_add_u64 v[86:87], v[248:249], 0, v[60:61]
	global_load_dwordx4 v[232:235], v[86:87], off
	global_load_dwordx4 v[148:151], v[86:87], off offset:64
	v_lshl_add_u64 v[86:87], v[248:249], 0, v[62:63]
	global_load_dwordx4 v[236:239], v[86:87], off
	global_load_dwordx4 v[152:155], v[86:87], off offset:64
	v_cmp_lt_i32_e64 s[0:1], v45, v47
	s_waitcnt lgkmcnt(1)
; __device__ __forceinline__ void gla_c_item(const Params& P, int item, unsigned char* smem) {
;     ...
;     for (int ks = 0; ks < 4; ++ks) {
;         const bf16x8 qb = *(const bf16x8*)(sQG + (16 * w + fr) * 136 + ks * 32 + fq * 8);
;         const bf16_t* SS = (ks >> 1) ? SS1 : SS0;
; #pragma unroll
;         for (int dvt = 0; dvt < 8; ++dvt) {
;             const bf16x8 sa = *(const bf16x8*)(SS + (size_t)(dvt * 16 + fr) * 64 + (ks & 1) * 32 + fq * 8);
;             oacc[dvt] = __builtin_amdgcn_mfma_f32_16x16x32_bf16(sa, qb, oacc[dvt], 0, 0, 0);
;         }
;     }
; #pragma unroll
;     for (int ks = 0; ks < 2; ++ks) {
;         const bf16x8 pb = *(const bf16x8*)(sP + (16 * w + fr) * LROW + ks * 32 + fq * 8);
; #pragma unroll
;         for (int dvt = 0; dvt < 8; ++dvt) {
;             const bf16x8 va = *(const bf16x8*)(sVt + (dvt * 16 + fr) * LROW + ks * 32 + fq * 8);
;             oacc[dvt] = __builtin_amdgcn_mfma_f32_16x16x32_bf16(va, pb, oacc[dvt], 0, 0, 0);
;         }
;     }
;     float ss = 0.f;
; #pragma unroll
;     for (int dvt = 0; dvt < 8; ++dvt)
; #pragma unroll
;         for (int r = 0; r < 4; ++r) ss += oacc[dvt][r] * oacc[dvt][r];
	s_waitcnt vmcnt(23)
	v_mfma_f32_16x16x32_bf16 v[4:7], v[4:7], v[82:85], 0
	s_waitcnt vmcnt(22)
	v_mfma_f32_16x16x32_bf16 v[8:11], v[8:11], v[82:85], 0
	v_cndmask_b32_e64 v45, v141, v45, s[0:1]
	s_waitcnt vmcnt(21)
	v_mfma_f32_16x16x32_bf16 v[12:15], v[12:15], v[82:85], 0
	v_lshlrev_b32_e32 v45, 2, v45
	s_waitcnt vmcnt(20)
	v_mfma_f32_16x16x32_bf16 v[16:19], v[16:19], v[82:85], 0
	s_waitcnt vmcnt(19)
	v_mfma_f32_16x16x32_bf16 v[20:23], v[20:23], v[82:85], 0
	s_waitcnt vmcnt(18)
	v_mfma_f32_16x16x32_bf16 v[24:27], v[24:27], v[82:85], 0
	s_waitcnt vmcnt(17)
	v_mfma_f32_16x16x32_bf16 v[28:31], v[28:31], v[82:85], 0
	s_waitcnt vmcnt(16)
	v_mfma_f32_16x16x32_bf16 v[0:3], v[0:3], v[82:85], 0
	ds_read_b128 v[82:85], v137 offset:28800
	s_waitcnt lgkmcnt(1)
	v_mfma_f32_16x16x32_bf16 v[4:7], v[176:179], v[144:147], v[4:7]
	v_mfma_f32_16x16x32_bf16 v[8:11], v[180:183], v[144:147], v[8:11]
	v_mfma_f32_16x16x32_bf16 v[12:15], v[184:187], v[144:147], v[12:15]
	v_mfma_f32_16x16x32_bf16 v[16:19], v[188:191], v[144:147], v[16:19]
	v_mfma_f32_16x16x32_bf16 v[20:23], v[192:195], v[144:147], v[20:23]
	v_mfma_f32_16x16x32_bf16 v[24:27], v[196:199], v[144:147], v[24:27]
	v_mfma_f32_16x16x32_bf16 v[28:31], v[200:203], v[144:147], v[28:31]
	v_mfma_f32_16x16x32_bf16 v[0:3], v[204:207], v[144:147], v[0:3]
	ds_read_b128 v[144:147], v137 offset:28864
	v_lshlrev_b32_e32 v86, 16, v34
	v_and_b32_e32 v87, 0xffff0000, v34
	s_waitcnt lgkmcnt(1)
	s_waitcnt vmcnt(15)
	v_mfma_f32_16x16x32_bf16 v[4:7], v[208:211], v[82:85], v[4:7]
	s_waitcnt vmcnt(13)
	v_mfma_f32_16x16x32_bf16 v[8:11], v[212:215], v[82:85], v[8:11]
	s_waitcnt vmcnt(11)
	v_mfma_f32_16x16x32_bf16 v[12:15], v[216:219], v[82:85], v[12:15]
	s_waitcnt vmcnt(9)
	v_mfma_f32_16x16x32_bf16 v[16:19], v[220:223], v[82:85], v[16:19]
	s_waitcnt vmcnt(7)
	v_mfma_f32_16x16x32_bf16 v[20:23], v[224:227], v[82:85], v[20:23]
	s_waitcnt vmcnt(5)
	v_mfma_f32_16x16x32_bf16 v[24:27], v[228:231], v[82:85], v[24:27]
	s_waitcnt vmcnt(3)
	v_mfma_f32_16x16x32_bf16 v[28:31], v[232:235], v[82:85], v[28:31]
	s_waitcnt vmcnt(1)
	v_mfma_f32_16x16x32_bf16 v[0:3], v[236:239], v[82:85], v[0:3]
	s_waitcnt vmcnt(0) lgkmcnt(0)
	v_mfma_f32_16x16x32_bf16 v[4:7], v[240:243], v[144:147], v[4:7]
	v_mfma_f32_16x16x32_bf16 v[8:11], v[244:247], v[144:147], v[8:11]
	v_mfma_f32_16x16x32_bf16 v[12:15], v[156:159], v[144:147], v[12:15]
	v_mfma_f32_16x16x32_bf16 v[16:19], v[160:163], v[144:147], v[16:19]
	v_mfma_f32_16x16x32_bf16 v[20:23], v[164:167], v[144:147], v[20:23]
	v_mfma_f32_16x16x32_bf16 v[24:27], v[172:175], v[144:147], v[24:27]
	v_mfma_f32_16x16x32_bf16 v[28:31], v[148:151], v[144:147], v[28:31]
	v_mfma_f32_16x16x32_bf16 v[0:3], v[152:155], v[144:147], v[0:3]
	ds_read_b128 v[82:85], v138 offset:46080
	ds_read_b128 v[144:147], v131 offset:55296
	s_waitcnt lgkmcnt(0)
	v_mfma_f32_16x16x32_bf16 v[4:7], v[144:147], v[82:85], v[4:7]
	ds_read_b128 v[144:147], v131 offset:57600
	s_waitcnt lgkmcnt(0)
	v_mfma_f32_16x16x32_bf16 v[8:11], v[144:147], v[82:85], v[8:11]
	ds_read_b128 v[144:147], v131 offset:59904
	s_waitcnt lgkmcnt(0)
	v_mfma_f32_16x16x32_bf16 v[12:15], v[144:147], v[82:85], v[12:15]
	ds_read_b128 v[144:147], v131 offset:62208
	s_waitcnt lgkmcnt(0)
	v_mfma_f32_16x16x32_bf16 v[16:19], v[144:147], v[82:85], v[16:19]
	ds_read_b128 v[144:147], v131 offset:64512
	s_waitcnt lgkmcnt(0)
	v_mfma_f32_16x16x32_bf16 v[144:147], v[144:147], v[82:85], v[20:23]
	s_nop 2
	ds_read_b128 v[20:23], v139 offset:11520
	s_waitcnt lgkmcnt(0)
	v_mfma_f32_16x16x32_bf16 v[148:151], v[20:23], v[82:85], v[24:27]
	ds_read_b128 v[20:23], v139 offset:13824
	s_waitcnt lgkmcnt(0)
	v_mfma_f32_16x16x32_bf16 v[152:155], v[20:23], v[82:85], v[28:31]
	ds_read_b128 v[20:23], v139 offset:16128
	s_waitcnt lgkmcnt(0)
	v_mfma_f32_16x16x32_bf16 v[0:3], v[20:23], v[82:85], v[0:3]
	ds_read_b128 v[82:85], v138 offset:46144
	ds_read_b128 v[20:23], v131 offset:55360
	s_waitcnt lgkmcnt(0)
	v_mfma_f32_16x16x32_bf16 v[28:31], v[20:23], v[82:85], v[4:7]
	s_nop 2
	ds_read_b128 v[4:7], v131 offset:57664
	s_waitcnt lgkmcnt(0)
	v_mfma_f32_16x16x32_bf16 v[24:27], v[4:7], v[82:85], v[8:11]
	ds_read_b128 v[4:7], v131 offset:59968
	s_nop 0
	v_mul_f32_e32 v33, v29, v29
	v_fmac_f32_e32 v33, v28, v28
	s_waitcnt lgkmcnt(0)
	v_mfma_f32_16x16x32_bf16 v[20:23], v[4:7], v[82:85], v[12:15]
	ds_read_b128 v[4:7], v131 offset:62272
	v_fmac_f32_e32 v33, v30, v30
	v_fmac_f32_e32 v33, v31, v31
	s_waitcnt lgkmcnt(0)
	v_mfma_f32_16x16x32_bf16 v[16:19], v[4:7], v[82:85], v[16:19]
	ds_read_b128 v[4:7], v131 offset:64576
	v_fmac_f32_e32 v33, v24, v24
	v_fmac_f32_e32 v33, v25, v25
	s_waitcnt lgkmcnt(0)
	v_mfma_f32_16x16x32_bf16 v[12:15], v[4:7], v[82:85], v[144:147]
	ds_read_b128 v[4:7], v140 offset:11520
	s_nop 1
	ds_read_b128 v[144:147], v140 offset:16128
	v_fmac_f32_e32 v33, v26, v26
	v_fmac_f32_e32 v33, v27, v27
	v_fmac_f32_e32 v33, v20, v20
	v_fmac_f32_e32 v33, v21, v21
	s_waitcnt lgkmcnt(1)
	v_mfma_f32_16x16x32_bf16 v[8:11], v[4:7], v[82:85], v[148:151]
	ds_read_b128 v[4:7], v140 offset:13824
	v_fmac_f32_e32 v33, v22, v22
	v_fmac_f32_e32 v33, v23, v23
	v_fmac_f32_e32 v33, v16, v16
	v_fmac_f32_e32 v33, v17, v17
	v_fmac_f32_e32 v33, v18, v18
	v_fmac_f32_e32 v33, v19, v19
	v_fmac_f32_e32 v33, v12, v12
	v_fmac_f32_e32 v33, v13, v13
	v_fmac_f32_e32 v33, v14, v14
	s_waitcnt lgkmcnt(0)
; __device__ __forceinline__ float bflo(unsigned u) { return __uint_as_float(u << 16); }
; __device__ __forceinline__ float bfhi(unsigned u) { return __uint_as_float(u & 0xffff0000u); }
; __device__ __forceinline__ float siluf_(float x) { return x * sigm(x); }
; __device__ __forceinline__ void store_bf4(bf16_t* p, f32x4 v) { uint2 o; o.x = pk2(v[0], v[1]); o.y = pk2(v[2], v[3]); *(uint2*)p = o; }
; __device__ __forceinline__ void gla_c_item(const Params& P, int item, unsigned char* smem) {
;     ...
;     float ss = 0.f;
; #pragma unroll
;     for (int dvt = 0; dvt < 8; ++dvt)
; #pragma unroll
;         for (int r = 0; r < 4; ++r) ss += oacc[dvt][r] * oacc[dvt][r];
;     ss += __shfl_xor(ss, 16); ss += __shfl_xor(ss, 32);
;     const float rinv = rsqrtf(ss * (1.f / 128.f) + 1e-6f);
; #pragma unroll
;     for (int dvt = 0; dvt < 8; ++dvt) {
;         const int dv = dvt * 16 + fq * 4;
;         const float rg[4] = {bflo(rgr[dvt].x), bfhi(rgr[dvt].x), bflo(rgr[dvt].y), bfhi(rgr[dvt].y)};
;         const f32x4 ng = *(const f32x4*)(P.in[25] + h * 128 + dv);
;         f32x4 o;
; #pragma unroll
;         for (int r = 0; r < 4; ++r) o[r] = oacc[dvt][r] * rinv * ng[r] * siluf_(rg[r]);
;         store_bf4(YB + (size_t)tok_out * 512 + h * 128 + dv, o);
	v_mfma_f32_16x16x32_bf16 v[4:7], v[4:7], v[82:85], v[152:155]
	v_fmac_f32_e32 v33, v15, v15
	v_fmac_f32_e32 v33, v8, v8
	v_fmac_f32_e32 v33, v9, v9
	v_fmac_f32_e32 v33, v10, v10
	v_mfma_f32_16x16x32_bf16 v[0:3], v[144:147], v[82:85], v[0:3]
	v_fmac_f32_e32 v33, v11, v11
	s_nop 1
	v_pk_mul_f32 v[84:85], v[4:5], v[4:5]
	v_pk_mul_f32 v[82:83], v[6:7], v[6:7]
	v_add_f32_e32 v33, v84, v33
	v_add_f32_e32 v33, v85, v33
	v_add_f32_e32 v33, v82, v33
	v_add_f32_e32 v33, v83, v33
	v_pk_mul_f32 v[84:85], v[0:1], v[0:1]
	v_pk_mul_f32 v[82:83], v[2:3], v[2:3]
	v_add_f32_e32 v33, v84, v33
	v_add_f32_e32 v33, v85, v33
	v_add_f32_e32 v33, v82, v33
	v_add_f32_e32 v33, v83, v33
	ds_bpermute_b32 v45, v45, v33
	v_lshlrev_b32_e32 v84, 16, v35
	v_and_b32_e32 v85, 0xffff0000, v35
	s_waitcnt lgkmcnt(0)
	v_add_f32_e32 v33, v33, v45
	v_xor_b32_e32 v45, 32, v141
	v_cmp_lt_i32_e64 s[0:1], v45, v47
	s_nop 1
	v_cndmask_b32_e64 v45, v141, v45, s[0:1]
	v_lshlrev_b32_e32 v45, 2, v45
	ds_bpermute_b32 v45, v45, v33
	s_waitcnt lgkmcnt(0)
	v_add_f32_e32 v33, v33, v45
	v_fmamk_f32 v33, v33, 0x3c000000, v142
	v_cmp_gt_f32_e64 s[0:1], s2, v33
	v_mul_f32_e32 v45, 0x4b800000, v33
	s_nop 0
	v_cndmask_b32_e64 v33, v33, v45, s[0:1]
	v_rsq_f32_e32 v33, v33
	s_nop 0
	v_mul_f32_e32 v45, 0x45800000, v33
	v_cndmask_b32_e64 v74, v33, v45, s[0:1]
	v_ashrrev_i32_e32 v33, 31, v32
	v_lshlrev_b64 v[32:33], 10, v[32:33]
	v_lshl_add_u64 v[32:33], s[88:89], 0, v[32:33]
	v_lshl_add_u64 v[82:83], v[32:33], 0, v[36:37]
	v_lshlrev_b32_e32 v36, 2, v80
	v_lshl_add_u64 v[80:81], v[42:43], 0, v[36:37]
	global_load_dwordx4 v[176:179], v[80:81], off
	global_load_dwordx4 v[180:183], v[80:81], off offset:64
	global_load_dwordx4 v[184:187], v[80:81], off offset:128
	global_load_dwordx4 v[188:191], v[80:81], off offset:192
	global_load_dwordx4 v[192:195], v[80:81], off offset:256
	global_load_dwordx4 v[196:199], v[80:81], off offset:320
	global_load_dwordx4 v[200:203], v[80:81], off offset:384
	global_load_dwordx4 v[204:207], v[80:81], off offset:448
	v_pk_mul_f32 v[28:29], v[28:29], v[74:75] op_sel_hi:[1,0]
	v_mul_f32_e32 v36, 0xbfb8aa3b, v86
	v_exp_f32_e32 v36, v36
	v_pk_mul_f32 v[30:31], v[30:31], v[74:75] op_sel_hi:[1,0]
	v_pk_mul_f32 v[24:25], v[24:25], v[74:75] op_sel_hi:[1,0]
	v_pk_mul_f32 v[26:27], v[26:27], v[74:75] op_sel_hi:[1,0]
	v_add_f32_e32 v36, 1.0, v36
	v_rcp_f32_e32 v144, v36
	v_pk_mul_f32 v[20:21], v[20:21], v[74:75] op_sel_hi:[1,0]
	v_pk_mul_f32 v[22:23], v[22:23], v[74:75] op_sel_hi:[1,0]
	v_pk_mul_f32 v[16:17], v[16:17], v[74:75] op_sel_hi:[1,0]
	v_pk_mul_f32 v[18:19], v[18:19], v[74:75] op_sel_hi:[1,0]
	v_pk_mul_f32 v[12:13], v[12:13], v[74:75] op_sel_hi:[1,0]
	v_pk_mul_f32 v[14:15], v[14:15], v[74:75] op_sel_hi:[1,0]
	v_pk_mul_f32 v[8:9], v[8:9], v[74:75] op_sel_hi:[1,0]
	v_pk_mul_f32 v[10:11], v[10:11], v[74:75] op_sel_hi:[1,0]
	v_pk_mul_f32 v[4:5], v[4:5], v[74:75] op_sel_hi:[1,0]
	v_pk_mul_f32 v[6:7], v[6:7], v[74:75] op_sel_hi:[1,0]
	v_pk_mul_f32 v[0:1], v[0:1], v[74:75] op_sel_hi:[1,0]
	v_pk_mul_f32 v[2:3], v[2:3], v[74:75] op_sel_hi:[1,0]
	s_waitcnt vmcnt(0)
	v_pk_mul_f32 v[28:29], v[176:177], v[28:29]
	v_mul_f32_e32 v32, 0xbfb8aa3b, v87
	v_exp_f32_e32 v32, v32
	v_pk_mul_f32 v[30:31], v[178:179], v[30:31]
	v_lshlrev_b32_e32 v34, 16, v78
	v_and_b32_e32 v35, 0xffff0000, v78
	v_add_f32_e32 v32, 1.0, v32
	v_rcp_f32_e32 v145, v32
	v_mul_f32_e32 v36, 0xbfb8aa3b, v34
	v_exp_f32_e32 v36, v36
	v_lshlrev_b32_e32 v78, 16, v79
	v_pk_mul_f32 v[32:33], v[144:145], v[86:87]
	v_and_b32_e32 v79, 0xffff0000, v79
	v_pk_mul_f32 v[32:33], v[32:33], v[28:29]
	v_mul_f32_e32 v28, 0xbfb8aa3b, v84
	v_mul_f32_e32 v29, 0xbfb8aa3b, v85
	v_exp_f32_e32 v28, v28
	v_exp_f32_e32 v29, v29
	v_cvt_pk_bf16_f32 v32, v32, v33
	v_add_f32_e32 v36, 1.0, v36
	v_add_f32_e32 v28, 1.0, v28
	v_add_f32_e32 v29, 1.0, v29
	v_rcp_f32_e32 v28, v28
	v_rcp_f32_e32 v29, v29
	s_nop 0
	v_pk_mul_f32 v[28:29], v[28:29], v[84:85]
	s_nop 0
	v_pk_mul_f32 v[30:31], v[28:29], v[30:31]
	v_lshl_add_u64 v[28:29], v[82:83], 0, v[48:49]
	v_cvt_pk_bf16_f32 v33, v30, v31
	global_store_dwordx2 v[28:29], v[32:33], off
	v_rcp_f32_e32 v82, v36
	v_pk_mul_f32 v[24:25], v[180:181], v[24:25]
	v_mul_f32_e32 v30, 0xbfb8aa3b, v35
	v_exp_f32_e32 v30, v30
	v_pk_mul_f32 v[26:27], v[182:183], v[26:27]
	v_lshlrev_b32_e32 v32, 16, v77
	v_and_b32_e32 v33, 0xffff0000, v77
	v_add_f32_e32 v30, 1.0, v30
	v_rcp_f32_e32 v83, v30
	s_nop 0
	v_pk_mul_f32 v[30:31], v[82:83], v[34:35]
	s_nop 0
	v_pk_mul_f32 v[24:25], v[30:31], v[24:25]
	v_mul_f32_e32 v30, 0xbfb8aa3b, v78
	v_mul_f32_e32 v31, 0xbfb8aa3b, v79
	v_exp_f32_e32 v30, v30
	v_exp_f32_e32 v31, v31
	v_cvt_pk_bf16_f32 v24, v24, v25
	v_add_f32_e32 v30, 1.0, v30
	v_add_f32_e32 v31, 1.0, v31
	v_rcp_f32_e32 v30, v30
	v_rcp_f32_e32 v31, v31
	s_nop 0
	v_pk_mul_f32 v[30:31], v[30:31], v[78:79]
	s_nop 0
	v_pk_mul_f32 v[26:27], v[30:31], v[26:27]
	v_lshlrev_b32_e32 v30, 16, v76
	v_cvt_pk_bf16_f32 v25, v26, v27
	global_store_dwordx2 v[28:29], v[24:25], off offset:32
	v_and_b32_e32 v31, 0xffff0000, v76
	v_mul_f32_e32 v34, 0xbfb8aa3b, v30
	v_exp_f32_e32 v34, v34
	v_pk_mul_f32 v[20:21], v[184:185], v[20:21]
	v_mul_f32_e32 v24, 0xbfb8aa3b, v31
	v_exp_f32_e32 v24, v24
	v_add_f32_e32 v34, 1.0, v34
	v_rcp_f32_e32 v34, v34
	v_pk_mul_f32 v[22:23], v[186:187], v[22:23]
	v_add_f32_e32 v24, 1.0, v24
	v_rcp_f32_e32 v35, v24
	v_lshlrev_b32_e32 v26, 16, v73
	v_and_b32_e32 v27, 0xffff0000, v73
; __device__ __forceinline__ float bflo(unsigned u) { return __uint_as_float(u << 16); }
; __device__ __forceinline__ float bfhi(unsigned u) { return __uint_as_float(u & 0xffff0000u); }
; __device__ __forceinline__ float siluf_(float x) { return x * sigm(x); }
; __device__ __forceinline__ void store_bf4(bf16_t* p, f32x4 v) { uint2 o; o.x = pk2(v[0], v[1]); o.y = pk2(v[2], v[3]); *(uint2*)p = o; }
; __device__ __forceinline__ void gla_c_item(const Params& P, int item, unsigned char* smem) {
;     ...
; #pragma unroll
;     for (int dvt = 0; dvt < 8; ++dvt) {
;         const int dv = dvt * 16 + fq * 4;
;         const float rg[4] = {bflo(rgr[dvt].x), bfhi(rgr[dvt].x), bflo(rgr[dvt].y), bfhi(rgr[dvt].y)};
;         const f32x4 ng = *(const f32x4*)(P.in[25] + h * 128 + dv);
;         f32x4 o;
; #pragma unroll
;         for (int r = 0; r < 4; ++r) o[r] = oacc[dvt][r] * rinv * ng[r] * siluf_(rg[r]);
;         store_bf4(YB + (size_t)tok_out * 512 + h * 128 + dv, o);
;     }
;     __syncthreads();
	v_pk_mul_f32 v[24:25], v[34:35], v[30:31]
	s_nop 0
	v_pk_mul_f32 v[20:21], v[24:25], v[20:21]
	v_mul_f32_e32 v24, 0xbfb8aa3b, v32
	v_mul_f32_e32 v25, 0xbfb8aa3b, v33
	v_exp_f32_e32 v24, v24
	v_exp_f32_e32 v25, v25
	v_cvt_pk_bf16_f32 v20, v20, v21
	v_add_f32_e32 v24, 1.0, v24
	v_add_f32_e32 v25, 1.0, v25
	v_rcp_f32_e32 v24, v24
	v_rcp_f32_e32 v25, v25
	s_nop 0
	v_pk_mul_f32 v[24:25], v[24:25], v[32:33]
	s_nop 0
	v_pk_mul_f32 v[22:23], v[24:25], v[22:23]
	v_lshlrev_b32_e32 v24, 16, v72
	v_cvt_pk_bf16_f32 v21, v22, v23
	global_store_dwordx2 v[28:29], v[20:21], off offset:64
	v_and_b32_e32 v25, 0xffff0000, v72
	v_mul_f32_e32 v30, 0xbfb8aa3b, v24
	v_exp_f32_e32 v30, v30
	v_pk_mul_f32 v[16:17], v[188:189], v[16:17]
	v_mul_f32_e32 v20, 0xbfb8aa3b, v25
	v_exp_f32_e32 v20, v20
	v_add_f32_e32 v30, 1.0, v30
	v_rcp_f32_e32 v30, v30
	v_pk_mul_f32 v[18:19], v[190:191], v[18:19]
	v_add_f32_e32 v20, 1.0, v20
	v_rcp_f32_e32 v31, v20
	v_lshlrev_b32_e32 v22, 16, v71
	v_and_b32_e32 v23, 0xffff0000, v71
	v_pk_mul_f32 v[20:21], v[30:31], v[24:25]
	s_nop 0
	v_pk_mul_f32 v[16:17], v[20:21], v[16:17]
	v_mul_f32_e32 v20, 0xbfb8aa3b, v26
	v_mul_f32_e32 v21, 0xbfb8aa3b, v27
	v_exp_f32_e32 v20, v20
	v_exp_f32_e32 v21, v21
	v_cvt_pk_bf16_f32 v16, v16, v17
	v_add_f32_e32 v20, 1.0, v20
	v_add_f32_e32 v21, 1.0, v21
	v_rcp_f32_e32 v20, v20
	v_rcp_f32_e32 v21, v21
	s_nop 0
	v_pk_mul_f32 v[20:21], v[20:21], v[26:27]
	s_nop 0
	v_pk_mul_f32 v[18:19], v[20:21], v[18:19]
	v_lshlrev_b32_e32 v20, 16, v70
	v_cvt_pk_bf16_f32 v17, v18, v19
	global_store_dwordx2 v[28:29], v[16:17], off offset:96
	v_and_b32_e32 v21, 0xffff0000, v70
	v_mul_f32_e32 v24, 0xbfb8aa3b, v20
	v_exp_f32_e32 v24, v24
	v_pk_mul_f32 v[12:13], v[192:193], v[12:13]
	v_mul_f32_e32 v16, 0xbfb8aa3b, v21
	v_exp_f32_e32 v16, v16
	v_add_f32_e32 v24, 1.0, v24
	v_rcp_f32_e32 v24, v24
	v_pk_mul_f32 v[14:15], v[194:195], v[14:15]
	v_add_f32_e32 v16, 1.0, v16
	v_rcp_f32_e32 v25, v16
	v_lshlrev_b32_e32 v18, 16, v69
	v_and_b32_e32 v19, 0xffff0000, v69
	v_pk_mul_f32 v[16:17], v[24:25], v[20:21]
	s_nop 0
	v_pk_mul_f32 v[12:13], v[16:17], v[12:13]
	v_mul_f32_e32 v16, 0xbfb8aa3b, v22
	v_mul_f32_e32 v17, 0xbfb8aa3b, v23
	v_exp_f32_e32 v16, v16
	v_exp_f32_e32 v17, v17
	v_cvt_pk_bf16_f32 v12, v12, v13
	v_add_f32_e32 v16, 1.0, v16
	v_add_f32_e32 v17, 1.0, v17
	v_rcp_f32_e32 v16, v16
	v_rcp_f32_e32 v17, v17
	s_nop 0
	v_pk_mul_f32 v[16:17], v[16:17], v[22:23]
	s_nop 0
	v_pk_mul_f32 v[14:15], v[16:17], v[14:15]
	v_lshlrev_b32_e32 v16, 16, v68
	v_cvt_pk_bf16_f32 v13, v14, v15
	global_store_dwordx2 v[28:29], v[12:13], off offset:128
	v_and_b32_e32 v17, 0xffff0000, v68
	v_mul_f32_e32 v20, 0xbfb8aa3b, v16
	v_exp_f32_e32 v20, v20
	v_pk_mul_f32 v[8:9], v[196:197], v[8:9]
	v_mul_f32_e32 v12, 0xbfb8aa3b, v17
	v_exp_f32_e32 v12, v12
	v_add_f32_e32 v20, 1.0, v20
	v_rcp_f32_e32 v20, v20
	v_pk_mul_f32 v[10:11], v[198:199], v[10:11]
	v_add_f32_e32 v12, 1.0, v12
	v_rcp_f32_e32 v21, v12
	v_lshlrev_b32_e32 v14, 16, v67
	v_and_b32_e32 v15, 0xffff0000, v67
	v_pk_mul_f32 v[12:13], v[20:21], v[16:17]
	s_nop 0
	v_pk_mul_f32 v[8:9], v[12:13], v[8:9]
	v_mul_f32_e32 v12, 0xbfb8aa3b, v18
	v_mul_f32_e32 v13, 0xbfb8aa3b, v19
	v_exp_f32_e32 v12, v12
	v_exp_f32_e32 v13, v13
	v_cvt_pk_bf16_f32 v8, v8, v9
	v_add_f32_e32 v12, 1.0, v12
	v_add_f32_e32 v13, 1.0, v13
	v_rcp_f32_e32 v12, v12
	v_rcp_f32_e32 v13, v13
	s_nop 0
	v_pk_mul_f32 v[12:13], v[12:13], v[18:19]
	s_nop 0
	v_pk_mul_f32 v[10:11], v[12:13], v[10:11]
	v_lshlrev_b32_e32 v12, 16, v66
	v_cvt_pk_bf16_f32 v9, v10, v11
	global_store_dwordx2 v[28:29], v[8:9], off offset:160
	v_and_b32_e32 v13, 0xffff0000, v66
	v_mul_f32_e32 v16, 0xbfb8aa3b, v12
	v_exp_f32_e32 v16, v16
	v_pk_mul_f32 v[4:5], v[200:201], v[4:5]
	v_mul_f32_e32 v8, 0xbfb8aa3b, v13
	v_exp_f32_e32 v8, v8
	v_add_f32_e32 v16, 1.0, v16
	v_rcp_f32_e32 v16, v16
	v_pk_mul_f32 v[6:7], v[202:203], v[6:7]
	v_add_f32_e32 v8, 1.0, v8
	v_rcp_f32_e32 v17, v8
	v_lshlrev_b32_e32 v10, 16, v65
	v_and_b32_e32 v11, 0xffff0000, v65
	v_pk_mul_f32 v[8:9], v[16:17], v[12:13]
	s_nop 0
	v_pk_mul_f32 v[4:5], v[8:9], v[4:5]
	v_mul_f32_e32 v8, 0xbfb8aa3b, v14
	v_mul_f32_e32 v9, 0xbfb8aa3b, v15
	v_exp_f32_e32 v8, v8
	v_exp_f32_e32 v9, v9
	v_cvt_pk_bf16_f32 v4, v4, v5
	v_add_f32_e32 v8, 1.0, v8
	v_add_f32_e32 v9, 1.0, v9
	v_rcp_f32_e32 v8, v8
	v_rcp_f32_e32 v9, v9
	s_nop 0
	v_pk_mul_f32 v[8:9], v[8:9], v[14:15]
	s_nop 0
	v_pk_mul_f32 v[6:7], v[8:9], v[6:7]
	v_lshlrev_b32_e32 v8, 16, v64
	v_cvt_pk_bf16_f32 v5, v6, v7
	global_store_dwordx2 v[28:29], v[4:5], off offset:192
	v_and_b32_e32 v9, 0xffff0000, v64
	v_mul_f32_e32 v12, 0xbfb8aa3b, v8
	v_exp_f32_e32 v12, v12
	v_pk_mul_f32 v[0:1], v[204:205], v[0:1]
	v_mul_f32_e32 v4, 0xbfb8aa3b, v9
	v_exp_f32_e32 v4, v4
	v_add_f32_e32 v12, 1.0, v12
	v_rcp_f32_e32 v12, v12
	v_pk_mul_f32 v[2:3], v[206:207], v[2:3]
	v_add_f32_e32 v4, 1.0, v4
	v_rcp_f32_e32 v13, v4
	s_nop 0
	v_pk_mul_f32 v[4:5], v[12:13], v[8:9]
	s_nop 0
	v_pk_mul_f32 v[0:1], v[4:5], v[0:1]
	v_mul_f32_e32 v4, 0xbfb8aa3b, v10
	v_mul_f32_e32 v5, 0xbfb8aa3b, v11
	v_exp_f32_e32 v4, v4
	v_exp_f32_e32 v5, v5
	v_cvt_pk_bf16_f32 v0, v0, v1
	v_add_f32_e32 v4, 1.0, v4
	v_add_f32_e32 v5, 1.0, v5
	v_rcp_f32_e32 v4, v4
	v_rcp_f32_e32 v5, v5
	s_nop 0
	v_pk_mul_f32 v[4:5], v[4:5], v[10:11]
	s_nop 0
	v_pk_mul_f32 v[2:3], v[4:5], v[2:3]
	s_nop 0
	v_cvt_pk_bf16_f32 v1, v2, v3
	global_store_dwordx2 v[28:29], v[0:1], off offset:224
	s_barrier
	s_cbranch_scc1 .LBB0_1340
